# adds q/k-norm + rope loop (phase 6): the row's K, gain and rope loads issued together at the top of the iteration
# baseline (speedup 1.0000x reference)
; __device__ __forceinline__ void qknorm_rope_phase(int gw, int NGW, int lane_in, bf16* QB, bf16* KB, const float* qkn, const f32x2* rope) {
;     ...
;     for (int it = 0;; ++it) { const int r = row_of(it, gw, NGW, MALL); if (r < 0) break; const int s = r % SB, b = r / SB;
; #pragma unroll
;         for (int hg = 3; hg < 4; ++hg) { const int Hh = 4 * hg + (lane >> 4);
;             bf16* base = hg < 3 ? QB + (size_t)r * 1536 + Hh * 128 : KB + ((size_t)(b * 4 + (Hh - 12)) * SB + s) * 128; const float* gn = qkn + (hg < 3 ? 0 : 128);
;             unsigned a[4]; float x[8];
; #pragma unroll
;             for (int q = 0; q < 4; ++q) { a[q] = *(const unsigned*)(base + 32 * q + 2 * j); x[2 * q] = bf2f(a[q] & 0xffffu); x[2 * q + 1] = bf2f(a[q] >> 16); }
;             float ss = 0.f;
; #pragma unroll
;             for (int e = 0; e < 8; ++e) ss += x[e] * x[e];
;             ss += __shfl_xor(ss, 1); ss += __shfl_xor(ss, 2); ss += __shfl_xor(ss, 4); ss += __shfl_xor(ss, 8);
;             const float rs = 1.f / sqrtf(ss * (1.f / 128.f) + EPS);
; #pragma unroll
;             for (int q = 0; q < 4; ++q) { x[2 * q] *= rs * gn[32 * q + 2 * j]; x[2 * q + 1] *= rs * gn[32 * q + 2 * j + 1]; }
;             if (s >= 256) { const f32x2* rp = rope + (size_t)(s - 256) * 64;
; #pragma unroll
;                 for (int ax = 0; ax < 2; ++ax)
; #pragma unroll
;                     for (int e = 0; e < 2; ++e) { const f32x2 cs = rp[ax * 32 + 2 * j + e]; const float x1 = x[4 * ax + e], x2 = x[4 * ax + 2 + e];
;                         x[4 * ax + e] = x1 * cs.x - x2 * cs.y; x[4 * ax + 2 + e] = x1 * cs.y + x2 * cs.x; } }
.LBB0_816:
	s_cmp_lt_i32 s0, 0
	s_cbranch_scc1 .LBB0_813
	s_mul_hi_u32 s4, s0, 0x3e0f83e1
	s_lshr_b32 s4, s4, 11
	s_mul_i32 s5, s4, 0x2100
	s_sub_i32 s0, s0, s5
	v_lshl_or_b32 v8, s4, 2, v24
	v_mov_b32_e32 v0, s0
	s_movk_i32 s4, 0x2100
	v_cmp_lt_i32_e32 vcc, v188, v185
	v_mad_u64_u32 v[8:9], s[4:5], v8, s4, v[0:1]
	s_nop 0
	v_cndmask_b32_e32 v0, v184, v188, vcc
	v_cmp_lt_i32_e32 vcc, v189, v185
	v_lshlrev_b64 v[8:9], 8, v[8:9]
	v_lshl_add_u64 v[8:9], v[2:3], 0, v[8:9]
	v_cndmask_b32_e32 v18, v184, v189, vcc
	v_cmp_lt_i32_e32 vcc, v187, v185
	global_load_dword v141, v[8:9], off
	global_load_dword v142, v[8:9], off offset:64
	global_load_dword v143, v[8:9], off offset:128
	global_load_dwordx2 v[144:145], v[4:5], off offset:512
	global_load_dwordx2 v[146:147], v[4:5], off offset:768
	global_load_dwordx2 v[148:149], v[4:5], off offset:896
	global_load_dwordx2 v[150:151], v[4:5], off offset:640
	v_mov_b32_e32 v160, s0
	v_add_u32_e32 v160, 0xffffff00, v160
	v_ashrrev_i32_e32 v161, 31, v160
	v_lshlrev_b64 v[160:161], 9, v[160:161]
	v_lshl_add_u64 v[162:163], v[160:161], 0, v[6:7]
	global_load_dwordx4 v[152:155], v[162:163], off
	global_load_dwordx4 v[156:159], v[162:163], off offset:256
	global_load_dword v12, v[8:9], off offset:192
	s_waitcnt vmcnt(2)
	v_lshlrev_b32_e32 v30, 2, v18
	v_cndmask_b32_e32 v22, v184, v187, vcc
	v_cmp_lt_i32_e32 vcc, v186, v185
	s_waitcnt vmcnt(1)
	v_lshlrev_b32_e32 v31, 2, v22
	v_lshlrev_b32_e32 v0, 2, v0
	v_cndmask_b32_e32 v10, v184, v186, vcc
	v_lshlrev_b32_e32 v27, 2, v10
	s_waitcnt vmcnt(0)
	v_mov_b32_e32 v10, v141
	s_mov_b32 s4, 0xf800000
	s_cmpk_lt_u32 s0, 0x100
	s_waitcnt vmcnt(1)
	v_lshlrev_b32_e32 v13, 16, v12
	v_and_b32_e32 v12, 0xffff0000, v12
	v_pk_mul_f32 v[20:21], v[12:13], v[12:13]
	s_waitcnt vmcnt(0)
	v_lshlrev_b32_e32 v16, 16, v10
	v_and_b32_e32 v17, 0xffff0000, v10
	v_mov_b32_e32 v10, v142
	v_pk_mul_f32 v[22:23], v[16:17], v[16:17]
	s_waitcnt vmcnt(0)
	v_lshlrev_b32_e32 v14, 16, v10
	v_and_b32_e32 v15, 0xffff0000, v10
	v_mov_b32_e32 v10, v143
	v_pk_mul_f32 v[28:29], v[14:15], v[14:15]
	v_add_f32_e32 v22, v22, v23
	v_add_f32_e32 v22, v22, v28
	v_add_f32_e32 v22, v29, v22
	s_waitcnt vmcnt(0)
	v_lshlrev_b32_e32 v11, 16, v10
	v_and_b32_e32 v10, 0xffff0000, v10
	v_pk_mul_f32 v[18:19], v[10:11], v[10:11]
	s_nop 0
	v_add_f32_e32 v19, v19, v22
	v_add_f32_e32 v18, v18, v19
	v_add_f32_e32 v18, v21, v18
	v_add_f32_e32 v18, v20, v18
	ds_bpermute_b32 v0, v0, v18
	s_waitcnt lgkmcnt(0)
	v_add_f32_e32 v0, v18, v0
	ds_bpermute_b32 v18, v30, v0
	s_waitcnt lgkmcnt(0)
	v_add_f32_e32 v0, v0, v18
	ds_bpermute_b32 v18, v31, v0
	s_waitcnt lgkmcnt(0)
	v_add_f32_e32 v0, v0, v18
	ds_bpermute_b32 v18, v27, v0
	s_waitcnt lgkmcnt(0)
	v_add_f32_e32 v0, v0, v18
	v_fmamk_f32 v0, v0, 0x3c000000, v25
	v_cmp_gt_f32_e32 vcc, s4, v0
	v_mul_f32_e32 v18, 0x4f800000, v0
	s_nop 0
	v_cndmask_b32_e32 v0, v0, v18, vcc
	v_sqrt_f32_e32 v18, v0
	s_nop 0
	v_add_u32_e32 v19, -1, v18
	v_fma_f32 v20, -v19, v18, v0
	v_cmp_ge_f32_e64 s[40:41], 0, v20
	v_add_u32_e32 v20, 1, v18
	s_nop 0
	v_cndmask_b32_e64 v19, v18, v19, s[40:41]
	v_fma_f32 v18, -v20, v18, v0
	v_cmp_lt_f32_e64 s[40:41], 0, v18
	s_nop 1
	v_cndmask_b32_e64 v18, v19, v20, s[40:41]
	v_mul_f32_e32 v19, 0x37800000, v18
	v_cndmask_b32_e32 v18, v18, v19, vcc
	v_cmp_class_f32_e32 vcc, v0, v26
	s_nop 1
	v_cndmask_b32_e32 v0, v18, v0, vcc
	v_div_scale_f32 v18, s[4:5], v0, v0, 1.0
	v_rcp_f32_e32 v19, v18
	s_nop 0
	v_fma_f32 v20, -v18, v19, 1.0
	v_fmac_f32_e32 v19, v20, v19
	v_div_scale_f32 v20, vcc, 1.0, v0, 1.0
	v_mul_f32_e32 v21, v20, v19
	v_fma_f32 v22, -v18, v21, v20
	v_fmac_f32_e32 v21, v22, v19
	v_fma_f32 v18, -v18, v21, v20
	v_div_fmas_f32 v18, v18, v19, v21
	v_div_fixup_f32 v0, v18, v0, 1.0
	v_mov_b32_e32 v18, v144
	v_mov_b32_e32 v19, v145
	v_mov_b32_e32 v20, v146
	v_mov_b32_e32 v21, v147
	v_mov_b32_e32 v22, v148
	v_mov_b32_e32 v23, v149
	s_waitcnt vmcnt(2)
	v_pk_mul_f32 v[18:19], v[18:19], v[0:1] op_sel_hi:[1,0]
	s_nop 0
	v_pk_mul_f32 v[18:19], v[18:19], v[16:17]
	v_mov_b32_e32 v16, v150
	v_mov_b32_e32 v17, v151
	s_waitcnt vmcnt(0)
	v_pk_mul_f32 v[16:17], v[16:17], v[0:1] op_sel_hi:[1,0]
	s_nop 0
	v_pk_mul_f32 v[14:15], v[16:17], v[14:15]
	v_mul_f32_e32 v16, v20, v0
	v_mul_f32_e32 v16, v16, v11
	v_mul_f32_e32 v11, v22, v0
	v_mov_b32_e32 v20, v23
	v_mul_f32_e32 v22, v11, v13
	v_pk_mul_f32 v[20:21], v[20:21], v[0:1] op_sel_hi:[1,0]
	v_mov_b32_e32 v13, v10
	v_pk_mul_f32 v[10:11], v[20:21], v[12:13]
	s_cbranch_scc1 .LBB0_819
	s_addk_i32 s0, 0xff00
	s_lshl_b64 s[4:5], s[0:1], 9
	v_lshl_add_u64 v[12:13], v[6:7], 0, s[4:5]
	v_mov_b32_e32 v28, v152
	v_mov_b32_e32 v29, v153
	v_mov_b32_e32 v30, v154
	v_mov_b32_e32 v31, v155
	v_mov_b32_e32 v17, v11
	v_mov_b32_e32 v23, v10
	s_waitcnt vmcnt(0)
	v_mov_b32_e32 v20, v28
	v_mov_b32_e32 v21, v30
	v_mov_b32_e32 v30, v29
	v_pk_mul_f32 v[28:29], v[14:15], v[30:31]
	v_pk_mul_f32 v[14:15], v[14:15], v[20:21]
	v_pk_fma_f32 v[28:29], v[18:19], v[20:21], v[28:29] neg_lo:[0,0,1] neg_hi:[0,0,1]
	v_pk_fma_f32 v[14:15], v[18:19], v[30:31], v[14:15]
	v_mov_b32_e32 v18, v156
	v_mov_b32_e32 v19, v157
	v_mov_b32_e32 v20, v158
	v_mov_b32_e32 v21, v159
	s_waitcnt vmcnt(0)
	v_mul_f32_e32 v12, v16, v19
	v_mul_f32_e32 v30, v22, v18
	v_mov_b32_e32 v32, v18
	v_mov_b32_e32 v18, v19
	v_mov_b32_e32 v19, v21
	v_pk_mul_f32 v[10:11], v[10:11], v[20:21]
	v_mov_b32_e32 v33, v20
	v_pk_mul_f32 v[18:19], v[22:23], v[18:19]
	v_mov_b32_e32 v13, v11
	v_mov_b32_e32 v31, v10
	v_pk_fma_f32 v[16:17], v[16:17], v[32:33], v[18:19] neg_lo:[0,0,1] neg_hi:[0,0,1]
	v_pk_add_f32 v[22:23], v[12:13], v[30:31]
	v_mov_b32_e32 v18, v28
	v_mov_b32_e32 v19, v29
	v_mov_b32_e32 v11, v17
	v_mov_b32_e32 v10, v23
